# attention softmax cross-row max via v_permlane16/32_swap instead of ds_bpermute (both query tiles side by side); code after attention kept at v041 addresses
# speedup vs baseline: 1.0436x; 1.0046x over previous
.LBB0_376:
	v_max3_f32 v107, v80, v81, v82
	v_max3_f32 v184, v64, v65, v66
	v_max3_f32 v107, v107, v83, v72
	v_max3_f32 v184, v184, v67, v68
	v_max3_f32 v107, v107, v73, v74
	v_max3_f32 v184, v184, v69, v70
	v_max3_f32 v107, v107, v75, v76
	v_max3_f32 v184, v184, v71, v60
	v_max3_f32 v107, v107, v77, v78
	v_max3_f32 v184, v184, v61, v62
	v_max3_f32 v107, v107, v79, v84
	v_max3_f32 v184, v184, v63, v56
	v_max3_f32 v107, v107, v85, v86
	v_max3_f32 v184, v184, v57, v58
	v_max_f32_e32 v107, v107, v87
	v_max_f32_e32 v184, v184, v59
	s_andn2_b64 vcc, exec, s[40:41]
	v_mov_b32_e32 v110, v107
	v_mov_b32_e32 v185, v184
	s_nop 0
	v_permlane16_swap_b32_e32 v110, v107
	v_permlane16_swap_b32_e32 v185, v184
	v_max_f32_e32 v107, v107, v110
	v_max_f32_e32 v184, v184, v185
	v_mov_b32_e32 v110, v107
	v_mov_b32_e32 v185, v184
	s_nop 0
	v_permlane32_swap_b32_e32 v110, v107
	v_permlane32_swap_b32_e32 v185, v184
	v_max3_f32 v107, v108, v107, v110
	v_sub_f32_e32 v108, v108, v107
	v_sub_f32_e32 v110, v80, v107
	v_exp_f32_e32 v80, v108
	v_sub_f32_e32 v81, v81, v107
	v_sub_f32_e32 v72, v72, v107
	v_exp_f32_e32 v124, v72
	v_pk_mul_f32 v[140:141], v[48:49], v[80:81] op_sel_hi:[1,0]
	v_pk_mul_f32 v[48:49], v[40:41], v[80:81] op_sel_hi:[1,0]
	v_pk_mul_f32 v[40:41], v[44:45], v[80:81] op_sel_hi:[1,0]
	v_sub_f32_e32 v72, v73, v107
	v_exp_f32_e32 v120, v72
	v_sub_f32_e32 v72, v74, v107
	v_exp_f32_e32 v118, v72
	v_sub_f32_e32 v72, v75, v107
	v_exp_f32_e32 v116, v72
	v_sub_f32_e32 v72, v76, v107
	v_exp_f32_e32 v114, v72
	v_sub_f32_e32 v72, v77, v107
	v_exp_f32_e32 v112, v72
	v_sub_f32_e32 v72, v78, v107
	v_exp_f32_e32 v130, v110
	v_exp_f32_e32 v110, v72
	v_sub_f32_e32 v72, v79, v107
	v_exp_f32_e32 v108, v72
	v_sub_f32_e32 v72, v84, v107
	v_sub_f32_e32 v82, v82, v107
	v_exp_f32_e32 v84, v72
	v_sub_f32_e32 v72, v85, v107
	v_exp_f32_e32 v122, v82
	v_exp_f32_e32 v82, v72
	v_sub_f32_e32 v72, v86, v107
	v_exp_f32_e32 v78, v72
	v_sub_f32_e32 v72, v87, v107
	v_max3_f32 v87, v109, v184, v185
	v_sub_f32_e32 v64, v64, v87
	v_exp_f32_e32 v131, v64
	v_sub_f32_e32 v64, v65, v87
	v_exp_f32_e32 v129, v64
	v_sub_f32_e32 v64, v66, v87
	v_exp_f32_e32 v123, v64
	v_sub_f32_e32 v64, v67, v87
	v_exp_f32_e32 v127, v64
	v_sub_f32_e32 v64, v68, v87
	v_exp_f32_e32 v125, v64
	v_sub_f32_e32 v64, v69, v87
	v_exp_f32_e32 v121, v64
	v_sub_f32_e32 v64, v70, v87
	v_sub_f32_e32 v83, v83, v107
	v_exp_f32_e32 v128, v81
	v_exp_f32_e32 v76, v72
	v_pk_mul_f32 v[142:143], v[50:51], v[80:81] op_sel_hi:[1,0]
	v_pk_mul_f32 v[74:75], v[54:55], v[80:81] op_sel_hi:[1,0]
	v_pk_mul_f32 v[72:73], v[52:53], v[80:81] op_sel_hi:[1,0]
	v_pk_mul_f32 v[50:51], v[42:43], v[80:81] op_sel_hi:[1,0]
	v_pk_mul_f32 v[42:43], v[46:47], v[80:81] op_sel_hi:[1,0]
	v_sub_f32_e32 v77, v109, v87
	v_exp_f32_e32 v119, v64
	v_sub_f32_e32 v64, v71, v87
	v_lshl_add_u32 v81, s36, 1, v135
	v_exp_f32_e32 v126, v83
	v_exp_f32_e32 v86, v77
	v_exp_f32_e32 v117, v64
	v_sub_f32_e32 v60, v60, v87
	ds_read_b64_tr_b16 v[66:67], v81 offset:20736
	ds_read_b64_tr_b16 v[64:65], v81 offset:18432
	ds_read_b64_tr_b16 v[68:69], v81 offset:18464
	ds_read_b64_tr_b16 v[70:71], v81 offset:20768
	v_exp_f32_e32 v115, v60
	v_sub_f32_e32 v60, v61, v87
	v_exp_f32_e32 v113, v60
	v_sub_f32_e32 v60, v62, v87
	v_exp_f32_e32 v111, v60
	v_sub_f32_e32 v60, v63, v87
	v_cvt_pk_bf16_f32 v52, v130, v128
	v_cvt_pk_bf16_f32 v53, v122, v126
	v_cvt_pk_bf16_f32 v54, v124, v120
	v_cvt_pk_bf16_f32 v55, v118, v116
	v_exp_f32_e32 v109, v60
	v_pk_mul_f32 v[14:15], v[14:15], v[86:87] op_sel_hi:[1,0]
	v_pk_mul_f32 v[12:13], v[12:13], v[86:87] op_sel_hi:[1,0]
	v_cvt_pk_bf16_f32 v60, v131, v129
	v_cvt_pk_bf16_f32 v61, v123, v127
	v_cvt_pk_bf16_f32 v62, v125, v121
	v_cvt_pk_bf16_f32 v63, v119, v117
	v_pk_mul_f32 v[10:11], v[10:11], v[86:87] op_sel_hi:[1,0]
	v_pk_mul_f32 v[8:9], v[8:9], v[86:87] op_sel_hi:[1,0]
	s_waitcnt lgkmcnt(2)
	v_mfma_f32_16x16x32_bf16 v[140:143], v[64:67], v[52:55], v[140:143]
	v_sub_f32_e32 v56, v56, v87
	v_exp_f32_e32 v85, v56
	v_sub_f32_e32 v56, v57, v87
	v_mfma_f32_16x16x32_bf16 v[12:15], v[64:67], v[60:63], v[12:15]
	ds_read_b64_tr_b16 v[64:65], v81 offset:18496
	ds_read_b64_tr_b16 v[66:67], v81 offset:20800
	v_pk_mul_f32 v[2:3], v[2:3], v[86:87] op_sel_hi:[1,0]
	v_pk_mul_f32 v[0:1], v[0:1], v[86:87] op_sel_hi:[1,0]
	s_waitcnt lgkmcnt(2)
	v_mfma_f32_16x16x32_bf16 v[72:75], v[68:71], v[52:55], v[72:75]
	v_mul_f32_e64 v6, v6, v86
	v_mul_f32_e64 v7, v7, v86
	v_pk_mul_f32 v[4:5], v[4:5], v[86:87] op_sel_hi:[1,0]
	v_exp_f32_e32 v83, v56
	v_mfma_f32_16x16x32_bf16 v[8:11], v[68:71], v[60:63], v[8:11]
	ds_read_b64_tr_b16 v[68:69], v81 offset:18528
	ds_read_b64_tr_b16 v[70:71], v81 offset:20832
	v_cvt_pk_bf16_f32 v44, v114, v112
	v_cvt_pk_bf16_f32 v45, v110, v108
	s_waitcnt lgkmcnt(2)
	v_mfma_f32_16x16x32_bf16 v[144:147], v[64:67], v[52:55], v[48:51]
	v_cvt_pk_bf16_f32 v46, v84, v82
	v_cvt_pk_bf16_f32 v47, v78, v76
	v_cvt_pk_bf16_f32 v56, v115, v113
	v_sub_f32_e32 v48, v58, v87
	s_waitcnt lgkmcnt(0)
	v_mfma_f32_16x16x32_bf16 v[148:151], v[68:71], v[52:55], v[40:43]
	v_exp_f32_e32 v79, v48
	v_cvt_pk_bf16_f32 v57, v111, v109
	v_cvt_pk_bf16_f32 v58, v85, v83
	v_sub_f32_e32 v40, v59, v87
	v_mfma_f32_16x16x32_bf16 v[0:3], v[64:67], v[60:63], v[0:3]
	ds_read_b64_tr_b16 v[64:65], v81 offset:23040
	ds_read_b64_tr_b16 v[66:67], v81 offset:25344
	v_exp_f32_e32 v77, v40
	ds_read_b64_tr_b16 v[40:41], v81 offset:23072
	ds_read_b64_tr_b16 v[42:43], v81 offset:25376
	v_mfma_f32_16x16x32_bf16 v[4:7], v[68:71], v[60:63], v[4:7]
	ds_read_b64_tr_b16 v[60:61], v81 offset:23104
	ds_read_b64_tr_b16 v[62:63], v81 offset:25408
	v_cvt_pk_bf16_f32 v59, v79, v77
	s_waitcnt lgkmcnt(2)
	v_mfma_f32_16x16x32_bf16 v[52:55], v[40:43], v[44:47], v[72:75]
	v_mfma_f32_16x16x32_bf16 v[8:11], v[40:43], v[56:59], v[8:11]
	s_waitcnt lgkmcnt(0)
	v_mfma_f32_16x16x32_bf16 v[40:43], v[60:63], v[44:47], v[144:147]
	v_mfma_f32_16x16x32_bf16 v[0:3], v[60:63], v[56:59], v[0:3]
	ds_read_b64_tr_b16 v[60:61], v81 offset:23136
	ds_read_b64_tr_b16 v[62:63], v81 offset:25440
	v_mfma_f32_16x16x32_bf16 v[48:51], v[64:67], v[44:47], v[140:143]
	v_mfma_f32_16x16x32_bf16 v[12:15], v[64:67], v[56:59], v[12:15]
	s_waitcnt lgkmcnt(0)
	v_mfma_f32_16x16x32_bf16 v[44:47], v[60:63], v[44:47], v[148:151]
	v_mfma_f32_16x16x32_bf16 v[4:7], v[60:63], v[56:59], v[4:7]
	s_cbranch_vccnz .LBB0_378
	s_lshl_b32 s0, s33, 6
	s_xor_b32 s0, s0, 64
	s_mulk_i32 s0, 0x90
	v_add_u32_e32 v56, s0, v103
	s_waitcnt vmcnt(1)
	ds_write_b128 v56, v[32:35]
	s_waitcnt vmcnt(0)
	ds_write_b128 v56, v[36:39] offset:18432

.LBB0_382:
	v_mov_b32_e32 v32, v221
	s_movk_i32 s0, 0x800
	s_barrier
	s_nop 0
	v_readfirstlane_b32 s16, v32
	v_cmp_gt_i32_e32 vcc, s0, v32
	v_lshlrev_b32_e32 v33, 3, v32
	s_barrier
	s_and_saveexec_b64 s[0:1], vcc
	v_readlane_b32 s4, v253, 63
	v_readlane_b32 s5, v254, 0
	s_movk_i32 s6, 0x110
	s_movk_i32 s17, 0x5ff
	s_cbranch_execz .LBB0_385
	s_mov_b64 s[10:11], 0
	v_mov_b32_e32 v0, v33
	v_mov_b32_e32 v1, v32
	s_nop 0
	s_nop 0
	s_nop 0
	s_nop 0
	s_nop 0
	s_nop 0
	s_nop 0
	s_nop 0
